# previous best + dilated edge-tile masks via precomputed additive -1e30 bias (fewer VALU)
# speedup vs baseline: 1.0053x; 1.0053x over previous
; DI int v_st64(int k, int c) { const int kk = (k & ~0xC) | ((k & 4) << 1) | ((k & 8) >> 1); return ((kk >> 3) * 2 + (c >> 5)) * 512 + ((kk & 7) * 32 + (c & 31)) * 2; }
; DI void unit(const bf16* __restrict__ QKV, const int* __restrict__ pos, bf16* __restrict__ OA, float* __restrict__ LSE,
;              int b, int h, int d, int r, int qb, float slope, char* lds) {
;     ...
;     for (int i = 0; i < 3; ++i) { const int idx = tid + (i0 + i) * 512, row = idx >> 3, ch = idx & 7, v = u0 - 64 + row; const bool ok = (v >= 0) && (v < L);
;       const unsigned go = (unsigned)((r + d * (ok ? v : 0)) * 64 + ch * 8) * 2u;
;       kreg[i] = *(const bf16x8*)((const char*)base + PLANE + go); vreg[i] = *(const bf16x8*)((const char*)base + 2 * PLANE + go);
;       if (!ok) { kreg[i] = bf16x8{}; vreg[i] = bf16x8{}; } }
; #pragma unroll
;     for (int i = 0; i < 3; ++i) { const int idx = tid + (i0 + i) * 512, row = idx >> 3, ch = idx & 7;
;       *(bf16x8*)(K_lds + PSWZ(row, ch * 16)) = kreg[i]; *(bf16x8*)(V_lds + v_st64(row, ch * 8)) = vreg[i]; }
;     ...
;       for (int j = 0; j < 4; ++j) { const int rr = 4 * g + j, kr = j + 8 * g + 4 * hi;
;         float sc = fmaf(__builtin_fabsf(pqf - pk4[j]), -sl2, p[ta][rr] * C);
;         if (ta == 0) sc = (kr >= r32) ? sc : -1e30f;
;         if (ta == 4) sc = (kr <= r32) ? sc : -1e30f;
.Ldil_noprio:
	s_cmpk_gt_i32 s33, 0xbff
	s_cbranch_scc1 .Ldil_done
	s_add_u32 s0, s26, 0x9c00000
	s_addc_u32 s1, s27, 0
	s_add_u32 s10, s26, 0xfc00000
	s_addc_u32 s11, s27, 0
	s_add_u32 s13, s26, 0x7400000
	s_addc_u32 s38, s27, 0
	s_mov_b32 s9, 0
	s_load_dwordx2 s[40:41], s[98:99], 0x10
	s_movk_i32 s39, 0x70
	s_movk_i32 s42, 0x180
	v_mov_b32_e32 v93, 0
	s_mov_b32 s43, 0x42fc0000
	s_movk_i32 s44, 0x60
	s_mov_b32 s45, 0xf149f2ca
	v_mov_b32_e32 v96, 0x42800000
	s_add_i32 s46, 0, 0x18000
	v_mov_b32_e32 v97, 0xf149f2ca
	v_lshrrev_b32_e32 v234, 3, v242
	v_lshlrev_b32_e32 v235, 4, v242
	v_and_b32_e32 v235, 0x70, v235
	v_lshrrev_b32_e32 v222, 1, v234
	v_and_b32_e32 v222, 7, v222
	v_lshlrev_b32_e32 v222, 4, v222
	v_xor_b32_e32 v222, v222, v235
	v_lshl_or_b32 v222, v234, 7, v222
	v_and_b32_e32 v223, 51, v234
	v_and_b32_e32 v224, 4, v234
	v_lshlrev_b32_e32 v224, 1, v224
	v_or_b32_e32 v223, v223, v224
	v_and_b32_e32 v224, 8, v234
	v_lshrrev_b32_e32 v224, 1, v224
	v_or_b32_e32 v223, v223, v224
	v_lshrrev_b32_e32 v224, 3, v223
	v_lshlrev_b32_e32 v224, 1, v224
	v_bfe_u32 v225, v242, 2, 1
	v_add_u32_e32 v224, v224, v225
	v_lshlrev_b32_e32 v224, 9, v224
	v_and_b32_e32 v225, 7, v223
	v_lshlrev_b32_e32 v225, 5, v225
	v_and_b32_e32 v226, 3, v242
	v_lshl_or_b32 v225, v226, 3, v225
	v_lshlrev_b32_e32 v225, 1, v225
	v_add_u32_e32 v223, v224, v225
	v_add_u32_e32 v223, 0xc000, v223
	v_and_b32_e32 v236, 31, v242
	v_bfe_u32 v237, v242, 5, 1
	v_lshlrev_b32_e32 v237, 2, v237
	v_mov_b32_e32 v238, 0xf149f2ca
	v_mov_b32_e32 v240, 0
	v_add_u32_e32 v239, 0, v237
	v_cmp_ge_u32_e32 vcc, v239, v236
	s_nop 1
	v_cndmask_b32_e32 v134, v238, v240, vcc
	v_add_u32_e32 v239, 1, v237
	v_cmp_ge_u32_e32 vcc, v239, v236
	s_nop 1
	v_cndmask_b32_e32 v135, v238, v240, vcc
	v_add_u32_e32 v239, 2, v237
	v_cmp_ge_u32_e32 vcc, v239, v236
	s_nop 1
	v_cndmask_b32_e32 v136, v238, v240, vcc
	v_add_u32_e32 v239, 3, v237
	v_cmp_ge_u32_e32 vcc, v239, v236
	s_nop 1
	v_cndmask_b32_e32 v137, v238, v240, vcc
	v_add_u32_e32 v239, 8, v237
	v_cmp_ge_u32_e32 vcc, v239, v236
	s_nop 1
	v_cndmask_b32_e32 v138, v238, v240, vcc
	v_add_u32_e32 v239, 9, v237
	v_cmp_ge_u32_e32 vcc, v239, v236
	s_nop 1
	v_cndmask_b32_e32 v139, v238, v240, vcc
	v_add_u32_e32 v239, 10, v237
	v_cmp_ge_u32_e32 vcc, v239, v236
	s_nop 1
	v_cndmask_b32_e32 v140, v238, v240, vcc
	v_add_u32_e32 v239, 11, v237
	v_cmp_ge_u32_e32 vcc, v239, v236
	s_nop 1
	v_cndmask_b32_e32 v141, v238, v240, vcc
	v_add_u32_e32 v239, 16, v237
	v_cmp_ge_u32_e32 vcc, v239, v236
	s_nop 1
	v_cndmask_b32_e32 v142, v238, v240, vcc
	v_add_u32_e32 v239, 17, v237
	v_cmp_ge_u32_e32 vcc, v239, v236
	s_nop 1
	v_cndmask_b32_e32 v143, v238, v240, vcc
	v_add_u32_e32 v239, 18, v237
	v_cmp_ge_u32_e32 vcc, v239, v236
	s_nop 1
	v_cndmask_b32_e32 v144, v238, v240, vcc
	v_add_u32_e32 v239, 19, v237
	v_cmp_ge_u32_e32 vcc, v239, v236
	s_nop 1
	v_cndmask_b32_e32 v145, v238, v240, vcc
	v_add_u32_e32 v239, 24, v237
	v_cmp_ge_u32_e32 vcc, v239, v236
	s_nop 1
	v_cndmask_b32_e32 v148, v238, v240, vcc
	v_add_u32_e32 v239, 25, v237
	v_cmp_ge_u32_e32 vcc, v239, v236
	s_nop 1
	v_cndmask_b32_e32 v149, v238, v240, vcc
	v_add_u32_e32 v239, 26, v237
	v_cmp_ge_u32_e32 vcc, v239, v236
	s_nop 1
	v_cndmask_b32_e32 v150, v238, v240, vcc
	v_add_u32_e32 v239, 27, v237
	v_cmp_ge_u32_e32 vcc, v239, v236
	s_nop 1
	v_cndmask_b32_e32 v152, v238, v240, vcc
	v_add_u32_e32 v239, 0, v237
	v_cmp_le_u32_e32 vcc, v239, v236
	s_nop 1
	v_cndmask_b32_e32 v153, v238, v240, vcc
	v_add_u32_e32 v239, 1, v237
	v_cmp_le_u32_e32 vcc, v239, v236
	s_nop 1
	v_cndmask_b32_e32 v154, v238, v240, vcc
	v_add_u32_e32 v239, 2, v237
	v_cmp_le_u32_e32 vcc, v239, v236
	s_nop 1
	v_cndmask_b32_e32 v155, v238, v240, vcc
	v_add_u32_e32 v239, 3, v237
	v_cmp_le_u32_e32 vcc, v239, v236
	s_nop 1
	v_cndmask_b32_e32 v156, v238, v240, vcc
	v_add_u32_e32 v239, 8, v237
	v_cmp_le_u32_e32 vcc, v239, v236
	s_nop 1
	v_cndmask_b32_e32 v157, v238, v240, vcc
	v_add_u32_e32 v239, 9, v237
	v_cmp_le_u32_e32 vcc, v239, v236
	s_nop 1
	v_cndmask_b32_e32 v158, v238, v240, vcc
	v_add_u32_e32 v239, 10, v237
	v_cmp_le_u32_e32 vcc, v239, v236
	s_nop 1
	v_cndmask_b32_e32 v159, v238, v240, vcc
	v_add_u32_e32 v239, 11, v237
	v_cmp_le_u32_e32 vcc, v239, v236
	s_nop 1
	v_cndmask_b32_e32 v162, v238, v240, vcc
	v_add_u32_e32 v239, 16, v237
	v_cmp_le_u32_e32 vcc, v239, v236
	s_nop 1
	v_cndmask_b32_e32 v163, v238, v240, vcc
	v_add_u32_e32 v239, 17, v237
	v_cmp_le_u32_e32 vcc, v239, v236
	s_nop 1
	v_cndmask_b32_e32 v227, v238, v240, vcc
	v_add_u32_e32 v239, 18, v237
	v_cmp_le_u32_e32 vcc, v239, v236
	s_nop 1
	v_cndmask_b32_e32 v228, v238, v240, vcc
	v_add_u32_e32 v239, 19, v237
	v_cmp_le_u32_e32 vcc, v239, v236
	s_nop 1
	v_cndmask_b32_e32 v229, v238, v240, vcc
	v_add_u32_e32 v239, 24, v237
	v_cmp_le_u32_e32 vcc, v239, v236
	s_nop 1
	v_cndmask_b32_e32 v230, v238, v240, vcc
	v_add_u32_e32 v239, 25, v237
	v_cmp_le_u32_e32 vcc, v239, v236
	s_nop 1
	v_cndmask_b32_e32 v231, v238, v240, vcc
	v_add_u32_e32 v239, 26, v237
	v_cmp_le_u32_e32 vcc, v239, v236
	s_nop 1
	v_cndmask_b32_e32 v232, v238, v240, vcc
	v_add_u32_e32 v239, 27, v237
	v_cmp_le_u32_e32 vcc, v239, v236
	s_nop 1
	v_cndmask_b32_e32 v233, v238, v240, vcc
	s_waitcnt lgkmcnt(0)
	s_mov_b32 s47, s33
	s_branch .LBB0_858

; __device__ __forceinline__ int opaque_tid() { int t = threadIdx.x; asm volatile("" : "+v"(t)); return t; }
; #define SBAR() __builtin_amdgcn_sched_barrier(0)
; DI int v_st64(int k, int c) { const int kk = (k & ~0xC) | ((k & 4) << 1) | ((k & 8) >> 1); return ((kk >> 3) * 2 + (c >> 5)) * 512 + ((kk & 7) * 32 + (c & 31)) * 2; }
; DI void unit(const bf16* __restrict__ QKV, const int* __restrict__ pos, bf16* __restrict__ OA, float* __restrict__ LSE,
;              int b, int h, int d, int r, int qb, float slope, char* lds) {
;   const int tid = opaque_tid(), wid = tid >> 6, lane = tid & 63, r32 = lane & 31, hi = lane >> 5;
;   const int L = SEQ / d, u0 = qb * 256;
;   char* K_lds = lds + OFF_K; char* V_lds = lds + OFF_V; int* posk = (int*)(lds + OFF_POS); float* ws = (float*)(lds + OFF_WS) + wid * 64;
;   const bf16* base = QKV + (size_t)(b * 8 + h) * SEQ * 64;
;   constexpr size_t PLANE = (size_t)NB * 8 * SEQ * 64 * 2;
;   auto stage = [&](const int i0) {
;     bf16x8 kreg[3], vreg[3];
; #pragma unroll
;     for (int i = 0; i < 3; ++i) { const int idx = tid + (i0 + i) * 512, row = idx >> 3, ch = idx & 7, v = u0 - 64 + row; const bool ok = (v >= 0) && (v < L);
;       const unsigned go = (unsigned)((r + d * (ok ? v : 0)) * 64 + ch * 8) * 2u;
;       kreg[i] = *(const bf16x8*)((const char*)base + PLANE + go); vreg[i] = *(const bf16x8*)((const char*)base + 2 * PLANE + go);
;       if (!ok) { kreg[i] = bf16x8{}; vreg[i] = bf16x8{}; } }
; #pragma unroll
;     for (int i = 0; i < 3; ++i) { const int idx = tid + (i0 + i) * 512, row = idx >> 3, ch = idx & 7;
;       *(bf16x8*)(K_lds + PSWZ(row, ch * 16)) = kreg[i]; *(bf16x8*)(V_lds + v_st64(row, ch * 8)) = vreg[i]; }
;   };
;   stage(0); SBAR(); stage(3); SBAR();
;   float pkv = 3.0e8f; if (tid < 384) { const int v = u0 - 64 + tid; if (v >= 0 && v < L) pkv = (float)pos[b * SEQ + r + d * v]; }
;   const int uq = u0 + wid * 32 + r32, tq = r + d * uq;
;   bf16x8 qr[4];
; #pragma unroll
;   for (int d0 = 0; d0 < 4; ++d0) qr[d0] = *(const bf16x8*)((const char*)base + (unsigned)(tq * 64 + d0 * 16 + hi * 8) * 2u);
;   const int pq = pos[b * SEQ + tq];
;   if (tid < 384) ((float*)posk)[tid] = pkv;
;   __syncthreads();
.LBB0_864:
	s_and_b32 s48, s47, 7
	s_bfe_u32 s30, s47, 0x30007
	s_ff1_i32_b32 s3, s8
	s_lshr_b32 s49, 0x1000, s3
	s_lshl_b32 s31, s2, 8
	s_lshl_b32 s2, s48, 19
	s_lshl_b32 s3, s30, 22
	s_or_b32 s2, s3, s2
	s_add_u32 s16, s10, s2
	v_mov_b32_e32 v4, v242
	s_addc_u32 s17, s11, 0
	s_sub_i32 s50, s31, 64
	s_add_u32 s18, s16, 0x2000000
	s_addc_u32 s19, s17, 0
	s_add_u32 s20, s16, 0x4000000
	s_addc_u32 s21, s17, 0
	s_lshl_b32 s94, s30, 12
	s_or_b32 s94, s15, s94
	v_ashrrev_i32_e32 v6, 6, v4
	v_lshlrev_b32_e32 v102, 5, v6
	v_and_b32_e32 v100, 31, v4
	v_add_u32_e32 v0, s31, v102
	v_or_b32_e32 v0, v0, v100
	v_bfe_u32 v101, v4, 5, 1
	v_mul_lo_u32 v0, v0, s8
	v_add_u32_e32 v7, s15, v0
	v_lshlrev_b32_e32 v92, 4, v101
	v_lshl_or_b32 v8, v7, 7, v92
	v_lshl_add_u32 v94, s30, 12, v7
	global_load_dwordx4 v[0:3], v8, s[16:17]
	global_load_dwordx4 v[88:91], v8, s[16:17] offset:32
	global_load_dwordx4 v[84:87], v8, s[16:17] offset:64
	global_load_dwordx4 v[80:83], v8, s[16:17] offset:96
	v_ashrrev_i32_e32 v95, 31, v94
	v_lshl_add_u64 v[8:9], v[94:95], 2, s[40:41]
	global_load_dword v103, v[8:9], off
	v_add_u32_e32 v214, s50, v234
	s_add_i32 s95, s50, 64
	v_add_u32_e32 v215, s95, v234
	s_add_i32 s95, s50, 128
	v_add_u32_e32 v216, s95, v234
	s_add_i32 s95, s50, 192
	v_add_u32_e32 v217, s95, v234
	s_add_i32 s95, s50, 256
	v_add_u32_e32 v218, s95, v234
	s_add_i32 s95, s50, 320
	v_add_u32_e32 v219, s95, v234
	v_add_u32_e32 v220, s50, v4
	v_cmp_gt_u32_e64 s[80:81], s49, v214
	v_cmp_gt_u32_e64 s[82:83], s49, v215
	v_cmp_gt_u32_e64 s[84:85], s49, v216
	v_cmp_gt_u32_e64 s[86:87], s49, v217
	v_cmp_gt_u32_e64 s[88:89], s49, v218
	v_cmp_gt_u32_e64 s[90:91], s49, v219
	v_cmp_gt_u32_e64 s[92:93], s49, v220
	v_cmp_gt_i32_e32 vcc, s42, v4
	v_cndmask_b32_e64 v214, 0, v214, s[80:81]
	v_cndmask_b32_e64 v215, 0, v215, s[82:83]
	v_cndmask_b32_e64 v216, 0, v216, s[84:85]
	v_cndmask_b32_e64 v217, 0, v217, s[86:87]
	v_cndmask_b32_e64 v218, 0, v218, s[88:89]
	v_cndmask_b32_e64 v219, 0, v219, s[90:91]
	s_and_b64 s[92:93], s[92:93], vcc
	v_mul_lo_u32 v214, v214, s8
	v_mul_lo_u32 v215, v215, s8
	v_mul_lo_u32 v216, v216, s8
	v_mul_lo_u32 v217, v217, s8
	v_mul_lo_u32 v218, v218, s8
	v_mul_lo_u32 v219, v219, s8
	v_cndmask_b32_e64 v220, 0, v220, s[92:93]
	v_add_u32_e32 v214, s15, v214
	v_add_u32_e32 v215, s15, v215
	v_add_u32_e32 v216, s15, v216
	v_add_u32_e32 v217, s15, v217
	v_add_u32_e32 v218, s15, v218
	v_add_u32_e32 v219, s15, v219
	v_mul_lo_u32 v220, v220, s8
	v_lshl_or_b32 v214, v214, 7, v235
	v_lshl_or_b32 v215, v215, 7, v235
	v_lshl_or_b32 v216, v216, 7, v235
	v_lshl_or_b32 v217, v217, 7, v235
	v_lshl_or_b32 v218, v218, 7, v235
	v_lshl_or_b32 v219, v219, 7, v235
	v_add_lshl_u32 v220, v220, s94, 2
	global_load_dwordx4 v[164:167], v214, s[18:19]
	global_load_dwordx4 v[168:171], v214, s[20:21]
	global_load_dwordx4 v[172:175], v215, s[18:19]
	global_load_dwordx4 v[176:179], v215, s[20:21]
	global_load_dwordx4 v[180:183], v216, s[18:19]
	global_load_dwordx4 v[184:187], v216, s[20:21]
	global_load_dwordx4 v[188:191], v217, s[18:19]
	global_load_dwordx4 v[192:195], v217, s[20:21]
	global_load_dwordx4 v[196:199], v218, s[18:19]
	global_load_dwordx4 v[200:203], v218, s[20:21]
	global_load_dwordx4 v[204:207], v219, s[18:19]
	global_load_dwordx4 v[208:211], v219, s[20:21]
	global_load_dword v213, v220, s[40:41]
	s_waitcnt vmcnt(11)
	v_cndmask_b32_e64 v164, 0, v164, s[80:81]
	v_cndmask_b32_e64 v165, 0, v165, s[80:81]
	v_cndmask_b32_e64 v166, 0, v166, s[80:81]
	v_cndmask_b32_e64 v167, 0, v167, s[80:81]
	v_cndmask_b32_e64 v168, 0, v168, s[80:81]
	v_cndmask_b32_e64 v169, 0, v169, s[80:81]
	v_cndmask_b32_e64 v170, 0, v170, s[80:81]
	v_cndmask_b32_e64 v171, 0, v171, s[80:81]
	ds_write_b128 v222, v[164:167]
	ds_write_b128 v223, v[168:171]
	s_waitcnt vmcnt(9)
	v_cndmask_b32_e64 v172, 0, v172, s[82:83]
	v_cndmask_b32_e64 v173, 0, v173, s[82:83]
	v_cndmask_b32_e64 v174, 0, v174, s[82:83]
	v_cndmask_b32_e64 v175, 0, v175, s[82:83]
	v_cndmask_b32_e64 v176, 0, v176, s[82:83]
	v_cndmask_b32_e64 v177, 0, v177, s[82:83]
	v_cndmask_b32_e64 v178, 0, v178, s[82:83]
	v_cndmask_b32_e64 v179, 0, v179, s[82:83]
	ds_write_b128 v222, v[172:175] offset:8192
	ds_write_b128 v223, v[176:179] offset:8192
	s_waitcnt vmcnt(7)
	v_cndmask_b32_e64 v180, 0, v180, s[84:85]
	v_cndmask_b32_e64 v181, 0, v181, s[84:85]
	v_cndmask_b32_e64 v182, 0, v182, s[84:85]
	v_cndmask_b32_e64 v183, 0, v183, s[84:85]
	v_cndmask_b32_e64 v184, 0, v184, s[84:85]
	v_cndmask_b32_e64 v185, 0, v185, s[84:85]
	v_cndmask_b32_e64 v186, 0, v186, s[84:85]
	v_cndmask_b32_e64 v187, 0, v187, s[84:85]
	ds_write_b128 v222, v[180:183] offset:16384
	ds_write_b128 v223, v[184:187] offset:16384
	s_waitcnt vmcnt(5)
	v_cndmask_b32_e64 v188, 0, v188, s[86:87]
	v_cndmask_b32_e64 v189, 0, v189, s[86:87]
	v_cndmask_b32_e64 v190, 0, v190, s[86:87]
	v_cndmask_b32_e64 v191, 0, v191, s[86:87]
	v_cndmask_b32_e64 v192, 0, v192, s[86:87]
	v_cndmask_b32_e64 v193, 0, v193, s[86:87]
	v_cndmask_b32_e64 v194, 0, v194, s[86:87]
	v_cndmask_b32_e64 v195, 0, v195, s[86:87]
	ds_write_b128 v222, v[188:191] offset:24576
	ds_write_b128 v223, v[192:195] offset:24576
	s_waitcnt vmcnt(3)
	v_cndmask_b32_e64 v196, 0, v196, s[88:89]
	v_cndmask_b32_e64 v197, 0, v197, s[88:89]
	v_cndmask_b32_e64 v198, 0, v198, s[88:89]
	v_cndmask_b32_e64 v199, 0, v199, s[88:89]
	v_cndmask_b32_e64 v200, 0, v200, s[88:89]
	v_cndmask_b32_e64 v201, 0, v201, s[88:89]
	v_cndmask_b32_e64 v202, 0, v202, s[88:89]
	v_cndmask_b32_e64 v203, 0, v203, s[88:89]
	ds_write_b128 v222, v[196:199] offset:32768
	ds_write_b128 v223, v[200:203] offset:32768
	s_waitcnt vmcnt(1)
	v_cndmask_b32_e64 v204, 0, v204, s[90:91]
	v_cndmask_b32_e64 v205, 0, v205, s[90:91]
	v_cndmask_b32_e64 v206, 0, v206, s[90:91]
	v_cndmask_b32_e64 v207, 0, v207, s[90:91]
	v_cndmask_b32_e64 v208, 0, v208, s[90:91]
	v_cndmask_b32_e64 v209, 0, v209, s[90:91]
	v_cndmask_b32_e64 v210, 0, v210, s[90:91]
	v_cndmask_b32_e64 v211, 0, v211, s[90:91]
	ds_write_b128 v222, v[204:207] offset:40960
	ds_write_b128 v223, v[208:211] offset:40960
	s_waitcnt vmcnt(0)
	v_cmp_gt_i32_e32 vcc, s42, v4
	v_cvt_f32_i32_e32 v213, v213
	v_mov_b32_e32 v5, 0x4d8f0d18
	v_cndmask_b32_e64 v5, v5, v213, s[92:93]
	s_and_saveexec_b64 s[2:3], vcc
	v_lshl_add_u32 v7, v4, 2, 0
	v_add_u32_e32 v7, 0x18000, v7
	ds_write_b32 v7, v5
	s_or_b64 exec, exec, s[2:3]
	v_lshlrev_b32_e32 v5, 3, v4
	v_lshlrev_b32_e32 v99, 12, v6
	v_bitop3_b32 v7, v92, v5, s39 bitop3:0x78
	v_lshl_or_b32 v14, v100, 7, v99
	v_add3_u32 v15, 0, v7, v14
	s_waitcnt lgkmcnt(0)
	s_barrier
; #define SBAR() __builtin_amdgcn_sched_barrier(0)
; DI void unit(const bf16* __restrict__ QKV, const int* __restrict__ pos, bf16* __restrict__ OA, float* __restrict__ LSE,
;              int b, int h, int d, int r, int qb, float slope, char* lds) {
;     ...
;   f32x16 p[5];
; #pragma unroll
;   for (int ta = 0; ta < 5; ++ta) { p[ta] = f32x16{};
; #pragma unroll
;     for (int d0 = 0; d0 < 4; ++d0) { const bf16x8 a = *(const bf16x8*)(K_lds + PSWZ(wid * 32 + ta * 32 + r32, (d0 * 16 + hi * 8) * 2));
;       p[ta] = __builtin_amdgcn_mfma_f32_32x32x16_bf16(a, qr[d0], p[ta], 0, 0, 0); }
;     SBAR(); }
;   const float C = 0.125f * 1.4426950408889634f, sl2 = slope * 1.4426950408889634f;
;   const float* pbase = (const float*)posk + wid * 32 + 4 * hi; const float pqf = (float)pq;
;   float mx = -1e30f;
; #pragma unroll
;   for (int ta = 0; ta < 5; ++ta) {
; #pragma unroll
;     for (int g = 0; g < 4; ++g) { const f32x4 pk4 = *(const f32x4*)(pbase + ta * 32 + 8 * g);
; #pragma unroll
;       for (int j = 0; j < 4; ++j) { const int rr = 4 * g + j, kr = j + 8 * g + 4 * hi;
;         float sc = fmaf(__builtin_fabsf(pqf - pk4[j]), -sl2, p[ta][rr] * C);
;         if (ta == 0) sc = (kr >= r32) ? sc : -1e30f;
;         if (ta == 4) sc = (kr <= r32) ? sc : -1e30f;
;         p[ta][rr] = sc; mx = fmaxf(mx, sc); } }
	ds_read_b128 v[6:9], v15
	v_and_b32_e32 v5, 0x70, v5
	v_bitop3_b32 v10, v92, v5, 32 bitop3:0x36
	v_add3_u32 v104, 0, v10, v14
	ds_read_b128 v[10:13], v104
	s_waitcnt vmcnt(4) lgkmcnt(1)
	v_mfma_f32_32x32x16_bf16 v[64:79], v[6:9], v[0:3], 0
	v_bitop3_b32 v6, v92, v5, 64 bitop3:0x36
	v_add3_u32 v108, 0, v6, v14
	ds_read_b128 v[6:9], v108
	v_bitop3_b32 v5, v92, v5, s44 bitop3:0x36
	v_add3_u32 v109, 0, v5, v14
	s_add_i32 s2, s48, 1
	v_cvt_f32_ubyte0_e32 v16, s2
	s_waitcnt vmcnt(3) lgkmcnt(1)
	v_mfma_f32_32x32x16_bf16 v[64:79], v[10:13], v[88:91], v[64:79]
	ds_read_b128 v[10:13], v109
	v_cmp_lt_f32_e32 vcc, s43, v16
	s_and_b64 s[2:3], vcc, exec
	s_cselect_b32 s2, 0xffffffc0, 0
	v_cndmask_b32_e32 v17, 0, v96, vcc
	v_sub_f32_e32 v5, v17, v16
	v_exp_f32_e32 v5, v5
	s_waitcnt vmcnt(2) lgkmcnt(1)
	v_mfma_f32_32x32x16_bf16 v[64:79], v[6:9], v[84:87], v[64:79]
	s_ashr_i32 s15, s14, 31
	v_and_b32_e32 v98, 63, v4
	v_ldexp_f32 v110, v5, s2
	s_waitcnt vmcnt(1) lgkmcnt(0)
	v_mfma_f32_32x32x16_bf16 v[64:79], v[10:13], v[80:83], v[64:79]
	ds_read_b128 v[4:7], v15 offset:4096
	ds_read_b128 v[8:11], v104 offset:4096
	s_waitcnt lgkmcnt(1)
	v_mfma_f32_32x32x16_bf16 v[48:63], v[4:7], v[0:3], 0
	s_waitcnt lgkmcnt(0)
	v_mfma_f32_32x32x16_bf16 v[48:63], v[8:11], v[88:91], v[48:63]
	ds_read_b128 v[4:7], v108 offset:4096
	ds_read_b128 v[8:11], v109 offset:4096
	s_waitcnt lgkmcnt(1)
	v_mfma_f32_32x32x16_bf16 v[48:63], v[4:7], v[84:87], v[48:63]
	s_waitcnt lgkmcnt(0)
	v_mfma_f32_32x32x16_bf16 v[48:63], v[8:11], v[80:83], v[48:63]
	ds_read_b128 v[4:7], v15 offset:8192
	ds_read_b128 v[8:11], v104 offset:8192
	s_waitcnt lgkmcnt(1)
	v_mfma_f32_32x32x16_bf16 v[32:47], v[4:7], v[0:3], 0
	s_waitcnt lgkmcnt(0)
	v_mfma_f32_32x32x16_bf16 v[32:47], v[8:11], v[88:91], v[32:47]
	ds_read_b128 v[4:7], v108 offset:8192
	ds_read_b128 v[8:11], v109 offset:8192
	s_waitcnt lgkmcnt(1)
	v_mfma_f32_32x32x16_bf16 v[32:47], v[4:7], v[84:87], v[32:47]
	s_waitcnt lgkmcnt(0)
	v_mfma_f32_32x32x16_bf16 v[32:47], v[8:11], v[80:83], v[32:47]
	ds_read_b128 v[4:7], v15 offset:12288
	ds_read_b128 v[8:11], v104 offset:12288
	s_waitcnt lgkmcnt(1)
	v_mfma_f32_32x32x16_bf16 v[16:31], v[4:7], v[0:3], 0
	s_waitcnt lgkmcnt(0)
	v_mfma_f32_32x32x16_bf16 v[16:31], v[8:11], v[88:91], v[16:31]
	ds_read_b128 v[4:7], v108 offset:12288
	ds_read_b128 v[8:11], v109 offset:12288
	s_waitcnt lgkmcnt(1)
	v_mfma_f32_32x32x16_bf16 v[16:31], v[4:7], v[84:87], v[16:31]
	s_waitcnt lgkmcnt(0)
	v_mfma_f32_32x32x16_bf16 v[16:31], v[8:11], v[80:83], v[16:31]
	ds_read_b128 v[4:7], v15 offset:16384
	ds_read_b128 v[104:107], v104 offset:16384
	s_waitcnt lgkmcnt(1)
	v_mfma_f32_32x32x16_bf16 v[0:15], v[4:7], v[0:3], 0
	s_waitcnt lgkmcnt(0)
	v_mfma_f32_32x32x16_bf16 v[0:15], v[104:107], v[88:91], v[0:15]
	ds_read_b128 v[88:91], v108 offset:16384
	ds_read_b128 v[104:107], v109 offset:16384
	s_waitcnt lgkmcnt(1)
	v_mfma_f32_32x32x16_bf16 v[0:15], v[88:91], v[84:87], v[0:15]
	s_waitcnt lgkmcnt(0)
	v_mfma_f32_32x32x16_bf16 v[0:15], v[104:107], v[80:83], v[0:15]
	v_lshlrev_b32_e32 v80, 2, v102
	v_add3_u32 v88, s46, v80, v92
	ds_read_b128 v[80:83], v88
	ds_read_b128 v[84:87], v88 offset:32
	s_waitcnt vmcnt(0)
	v_cvt_f32_i32_e32 v89, v103
	v_lshlrev_b32_e32 v90, 2, v101
	v_mul_f32_e32 v91, 0xbfb8aa3b, v110
	v_mul_f32_e32 v64, 0x3e38aa3b, v64
	s_waitcnt lgkmcnt(1)
	v_sub_f32_e32 v80, v89, v80
	v_fma_f32 v64, |v80|, v91, v64
	v_sub_f32_e32 v81, v89, v81
	v_mul_f32_e32 v65, 0x3e38aa3b, v65
	v_add_f32_e32 v80, v134, v64
	v_fma_f32 v65, |v81|, v91, v65
	v_mul_f32_e32 v66, 0x3e38aa3b, v66
	v_add_f32_e32 v81, v135, v65
	v_sub_f32_e32 v65, v89, v82
	v_fma_f32 v65, |v65|, v91, v66
	v_mul_f32_e32 v66, 0x3e38aa3b, v67
	v_add_f32_e32 v82, v136, v65
	v_sub_f32_e32 v65, v89, v83
	v_fma_f32 v65, |v65|, v91, v66
	v_mul_f32_e32 v66, 0x3e38aa3b, v68
	v_add_f32_e32 v83, v137, v65
	s_waitcnt lgkmcnt(0)
	v_sub_f32_e32 v65, v89, v84
	v_fma_f32 v65, |v65|, v91, v66
	v_mul_f32_e32 v66, 0x3e38aa3b, v69
	v_add_f32_e32 v84, v138, v65
	v_sub_f32_e32 v65, v89, v85
	v_max3_f32 v64, v80, s45, v81
	v_fma_f32 v65, |v65|, v91, v66
	v_max3_f32 v64, v64, v82, v83
	v_add_f32_e32 v85, v139, v65
	v_max3_f32 v68, v64, v84, v85
	v_sub_f32_e32 v64, v89, v86
	v_mul_f32_e32 v65, 0x3e38aa3b, v70
	v_fma_f32 v64, |v64|, v91, v65
	v_mul_f32_e32 v65, 0x3e38aa3b, v71
	v_add_f32_e32 v86, v140, v64
	v_sub_f32_e32 v64, v89, v87
	v_fma_f32 v69, |v64|, v91, v65
	ds_read_b128 v[64:67], v88 offset:64
	v_mul_f32_e32 v72, 0x3e38aa3b, v72
	v_add_f32_e32 v87, v141, v69
	v_max3_f32 v107, v68, v86, v87
	ds_read_b128 v[68:71], v88 offset:96
	s_waitcnt lgkmcnt(1)
	v_sub_f32_e32 v64, v89, v64
	v_fma_f32 v64, |v64|, v91, v72
	v_add_f32_e32 v72, v142, v64
	v_sub_f32_e32 v64, v89, v65
	v_mul_f32_e32 v65, 0x3e38aa3b, v73
	v_fma_f32 v64, |v64|, v91, v65
	v_sub_f32_e32 v65, v89, v66
	v_mul_f32_e32 v66, 0x3e38aa3b, v74
	v_add_f32_e32 v73, v143, v64
	v_max3_f32 v64, v107, v72, v73
	v_fma_f32 v65, |v65|, v91, v66
	v_mul_f32_e32 v66, 0x3e38aa3b, v75
	v_add_f32_e32 v74, v144, v65
	v_sub_f32_e32 v65, v89, v67
	v_fma_f32 v65, |v65|, v91, v66
	v_mul_f32_e32 v66, 0x3e38aa3b, v76
	v_add_f32_e32 v75, v145, v65
	s_waitcnt lgkmcnt(0)
	v_sub_f32_e32 v65, v89, v68
	v_fma_f32 v65, |v65|, v91, v66
	v_mul_f32_e32 v66, 0x3e38aa3b, v77
	v_add_f32_e32 v76, v148, v65
	v_sub_f32_e32 v65, v89, v69
	v_fma_f32 v65, |v65|, v91, v66
	v_mul_f32_e32 v66, 0x3e38aa3b, v78
	v_add_f32_e32 v77, v149, v65
	v_sub_f32_e32 v65, v89, v70
	v_fma_f32 v65, |v65|, v91, v66
	v_mul_f32_e32 v66, 0x3e38aa3b, v79
	v_max3_f32 v64, v64, v74, v75
	v_add_f32_e32 v78, v150, v65
	v_sub_f32_e32 v65, v89, v71
	v_fma_f32 v65, |v65|, v91, v66
	v_max3_f32 v64, v64, v76, v77
	s_nop 0
	v_add_f32_e32 v79, v152, v65
	v_max3_f32 v115, v64, v78, v79
	ds_read_b128 v[64:67], v88 offset:128
	ds_read_b128 v[68:71], v88 offset:160
	v_mul_f32_e32 v49, 0x3e38aa3b, v49
	v_mul_f32_e32 v50, 0x3e38aa3b, v50
	v_mul_f32_e32 v48, 0x3e38aa3b, v48
	s_waitcnt lgkmcnt(1)
; DI void unit(const bf16* __restrict__ QKV, const int* __restrict__ pos, bf16* __restrict__ OA, float* __restrict__ LSE,
;              int b, int h, int d, int r, int qb, float slope, char* lds) {
;     ...
;   for (int ta = 0; ta < 5; ++ta) {
; #pragma unroll
;     for (int g = 0; g < 4; ++g) { const f32x4 pk4 = *(const f32x4*)(pbase + ta * 32 + 8 * g);
; #pragma unroll
;       for (int j = 0; j < 4; ++j) { const int rr = 4 * g + j, kr = j + 8 * g + 4 * hi;
;         float sc = fmaf(__builtin_fabsf(pqf - pk4[j]), -sl2, p[ta][rr] * C);
;         if (ta == 0) sc = (kr >= r32) ? sc : -1e30f;
;         if (ta == 4) sc = (kr <= r32) ? sc : -1e30f;
;         p[ta][rr] = sc; mx = fmaxf(mx, sc); } }
	v_sub_f32_e32 v65, v89, v65
	v_fma_f32 v65, |v65|, v91, v49
	v_sub_f32_e32 v49, v89, v66
	v_sub_f32_e32 v64, v89, v64
	v_fma_f32 v66, |v49|, v91, v50
	v_sub_f32_e32 v49, v89, v67
	v_mul_f32_e32 v50, 0x3e38aa3b, v51
	v_fma_f32 v64, |v64|, v91, v48
	v_fma_f32 v67, |v49|, v91, v50
	s_waitcnt lgkmcnt(0)
	v_sub_f32_e32 v49, v89, v68
	v_mul_f32_e32 v50, 0x3e38aa3b, v52
	v_max3_f32 v48, v115, v64, v65
	v_fma_f32 v68, |v49|, v91, v50
	v_sub_f32_e32 v49, v89, v69
	v_mul_f32_e32 v50, 0x3e38aa3b, v53
	v_max3_f32 v48, v48, v66, v67
	v_fma_f32 v69, |v49|, v91, v50
	v_max3_f32 v52, v48, v68, v69
	v_sub_f32_e32 v48, v89, v70
	v_mul_f32_e32 v49, 0x3e38aa3b, v54
	v_fma_f32 v70, |v48|, v91, v49
	ds_read_b128 v[48:51], v88 offset:192
	v_sub_f32_e32 v53, v89, v71
	v_mul_f32_e32 v54, 0x3e38aa3b, v55
	v_fma_f32 v71, |v53|, v91, v54
	v_max3_f32 v115, v52, v70, v71
	ds_read_b128 v[52:55], v88 offset:224
	s_waitcnt lgkmcnt(1)
	v_sub_f32_e32 v48, v89, v48
	v_mul_f32_e32 v56, 0x3e38aa3b, v56
	v_fma_f32 v56, |v48|, v91, v56
	v_sub_f32_e32 v48, v89, v49
	v_mul_f32_e32 v49, 0x3e38aa3b, v57
	v_fma_f32 v57, |v48|, v91, v49
	v_sub_f32_e32 v49, v89, v50
	v_mul_f32_e32 v50, 0x3e38aa3b, v58
	v_fma_f32 v58, |v49|, v91, v50
	v_sub_f32_e32 v49, v89, v51
	v_mul_f32_e32 v50, 0x3e38aa3b, v59
	v_fma_f32 v59, |v49|, v91, v50
	s_waitcnt lgkmcnt(0)
	v_sub_f32_e32 v49, v89, v52
	v_mul_f32_e32 v50, 0x3e38aa3b, v60
	v_fma_f32 v60, |v49|, v91, v50
	v_sub_f32_e32 v49, v89, v53
	v_mul_f32_e32 v50, 0x3e38aa3b, v61
	v_max3_f32 v48, v115, v56, v57
	v_fma_f32 v61, |v49|, v91, v50
	v_sub_f32_e32 v49, v89, v54
	v_mul_f32_e32 v50, 0x3e38aa3b, v62
	v_max3_f32 v48, v48, v58, v59
	v_fma_f32 v62, |v49|, v91, v50
	v_sub_f32_e32 v49, v89, v55
	v_mul_f32_e32 v50, 0x3e38aa3b, v63
	v_max3_f32 v48, v48, v60, v61
	v_fma_f32 v63, |v49|, v91, v50
	v_max3_f32 v115, v48, v62, v63
	ds_read_b128 v[48:51], v88 offset:256
	ds_read_b128 v[52:55], v88 offset:288
	v_mul_f32_e32 v33, 0x3e38aa3b, v33
	v_mul_f32_e32 v34, 0x3e38aa3b, v34
	v_mul_f32_e32 v32, 0x3e38aa3b, v32
	s_waitcnt lgkmcnt(1)
	v_sub_f32_e32 v49, v89, v49
	v_fma_f32 v49, |v49|, v91, v33
	v_sub_f32_e32 v33, v89, v50
	v_sub_f32_e32 v48, v89, v48
	v_fma_f32 v50, |v33|, v91, v34
	v_sub_f32_e32 v33, v89, v51
	v_mul_f32_e32 v34, 0x3e38aa3b, v35
	v_fma_f32 v48, |v48|, v91, v32
	v_fma_f32 v51, |v33|, v91, v34
	s_waitcnt lgkmcnt(0)
	v_sub_f32_e32 v33, v89, v52
	v_mul_f32_e32 v34, 0x3e38aa3b, v36
	v_max3_f32 v32, v115, v48, v49
	v_fma_f32 v52, |v33|, v91, v34
	v_sub_f32_e32 v33, v89, v53
	v_mul_f32_e32 v34, 0x3e38aa3b, v37
	v_max3_f32 v32, v32, v50, v51
	v_fma_f32 v53, |v33|, v91, v34
	v_max3_f32 v36, v32, v52, v53
	v_sub_f32_e32 v32, v89, v54
	v_mul_f32_e32 v33, 0x3e38aa3b, v38
	v_fma_f32 v54, |v32|, v91, v33
	ds_read_b128 v[32:35], v88 offset:320
	v_sub_f32_e32 v37, v89, v55
	v_mul_f32_e32 v38, 0x3e38aa3b, v39
	v_fma_f32 v55, |v37|, v91, v38
	v_max3_f32 v115, v36, v54, v55
	ds_read_b128 v[36:39], v88 offset:352
	s_waitcnt lgkmcnt(1)
	v_sub_f32_e32 v32, v89, v32
	v_mul_f32_e32 v40, 0x3e38aa3b, v40
	v_fma_f32 v40, |v32|, v91, v40
	v_sub_f32_e32 v32, v89, v33
	v_mul_f32_e32 v33, 0x3e38aa3b, v41
	v_fma_f32 v41, |v32|, v91, v33
	v_sub_f32_e32 v33, v89, v34
	v_mul_f32_e32 v34, 0x3e38aa3b, v42
	v_fma_f32 v42, |v33|, v91, v34
	v_sub_f32_e32 v33, v89, v35
	v_mul_f32_e32 v34, 0x3e38aa3b, v43
	v_fma_f32 v43, |v33|, v91, v34
	s_waitcnt lgkmcnt(0)
	v_sub_f32_e32 v33, v89, v36
	v_mul_f32_e32 v34, 0x3e38aa3b, v44
	v_fma_f32 v44, |v33|, v91, v34
	v_sub_f32_e32 v33, v89, v37
	v_mul_f32_e32 v34, 0x3e38aa3b, v45
	v_max3_f32 v32, v115, v40, v41
	v_fma_f32 v45, |v33|, v91, v34
	v_sub_f32_e32 v33, v89, v38
	v_mul_f32_e32 v34, 0x3e38aa3b, v46
	v_max3_f32 v32, v32, v42, v43
	v_fma_f32 v46, |v33|, v91, v34
	v_sub_f32_e32 v33, v89, v39
	v_mul_f32_e32 v34, 0x3e38aa3b, v47
	v_max3_f32 v32, v32, v44, v45
	v_fma_f32 v47, |v33|, v91, v34
	v_max3_f32 v115, v32, v46, v47
	ds_read_b128 v[32:35], v88 offset:384
	ds_read_b128 v[36:39], v88 offset:416
	v_mul_f32_e32 v17, 0x3e38aa3b, v17
	v_mul_f32_e32 v18, 0x3e38aa3b, v18
	v_mul_f32_e32 v16, 0x3e38aa3b, v16
	s_waitcnt lgkmcnt(1)
	v_sub_f32_e32 v33, v89, v33
	v_fma_f32 v33, |v33|, v91, v17
	v_sub_f32_e32 v17, v89, v34
	v_sub_f32_e32 v32, v89, v32
	v_fma_f32 v34, |v17|, v91, v18
	v_sub_f32_e32 v17, v89, v35
	v_mul_f32_e32 v18, 0x3e38aa3b, v19
	v_fma_f32 v116, |v32|, v91, v16
	v_fma_f32 v35, |v17|, v91, v18
	s_waitcnt lgkmcnt(0)
	v_sub_f32_e32 v17, v89, v36
	v_mul_f32_e32 v18, 0x3e38aa3b, v20
	v_max3_f32 v16, v115, v116, v33
	v_fma_f32 v36, |v17|, v91, v18
	v_sub_f32_e32 v17, v89, v37
	v_mul_f32_e32 v18, 0x3e38aa3b, v21
	v_max3_f32 v16, v16, v34, v35
	v_fma_f32 v37, |v17|, v91, v18
	v_max3_f32 v20, v16, v36, v37
	v_sub_f32_e32 v16, v89, v38
	v_mul_f32_e32 v17, 0x3e38aa3b, v22
	v_fma_f32 v38, |v16|, v91, v17
	ds_read_b128 v[16:19], v88 offset:448
	v_sub_f32_e32 v21, v89, v39
	v_mul_f32_e32 v22, 0x3e38aa3b, v23
	v_fma_f32 v39, |v21|, v91, v22
	v_max3_f32 v32, v20, v38, v39
	ds_read_b128 v[20:23], v88 offset:480
	s_waitcnt lgkmcnt(1)
	v_sub_f32_e32 v16, v89, v16
	v_mul_f32_e32 v24, 0x3e38aa3b, v24
	v_fma_f32 v24, |v16|, v91, v24
	v_sub_f32_e32 v16, v89, v17
	v_mul_f32_e32 v17, 0x3e38aa3b, v25
	v_fma_f32 v25, |v16|, v91, v17
	v_sub_f32_e32 v17, v89, v18
	v_mul_f32_e32 v18, 0x3e38aa3b, v26
	v_fma_f32 v26, |v17|, v91, v18
	v_sub_f32_e32 v17, v89, v19
	v_mul_f32_e32 v18, 0x3e38aa3b, v27
	v_fma_f32 v27, |v17|, v91, v18
	s_waitcnt lgkmcnt(0)
; #define SBAR() __builtin_amdgcn_sched_barrier(0)
; DI void unit(const bf16* __restrict__ QKV, const int* __restrict__ pos, bf16* __restrict__ OA, float* __restrict__ LSE,
;              int b, int h, int d, int r, int qb, float slope, char* lds) {
;     ...
;   for (int ta = 0; ta < 5; ++ta) {
; #pragma unroll
;     for (int g = 0; g < 4; ++g) { const f32x4 pk4 = *(const f32x4*)(pbase + ta * 32 + 8 * g);
; #pragma unroll
;       for (int j = 0; j < 4; ++j) { const int rr = 4 * g + j, kr = j + 8 * g + 4 * hi;
;         float sc = fmaf(__builtin_fabsf(pqf - pk4[j]), -sl2, p[ta][rr] * C);
;         if (ta == 0) sc = (kr >= r32) ? sc : -1e30f;
;         if (ta == 4) sc = (kr <= r32) ? sc : -1e30f;
;         p[ta][rr] = sc; mx = fmaxf(mx, sc); } }
;     SBAR(); }
;   { auto x = __builtin_amdgcn_permlane32_swap(__float_as_uint(mx), __float_as_uint(mx), false, false); mx = fmaxf(__uint_as_float(x[0]), __uint_as_float(x[1])); }
;   float ls = 0.f;
; #pragma unroll
;   for (int ta = 0; ta < 5; ++ta)
; #pragma unroll
;     for (int rr = 0; rr < 16; ++rr) { p[ta][rr] = __builtin_amdgcn_exp2f(p[ta][rr] - mx); ls += p[ta][rr]; if (rr == 15) SBAR(); }
;   { auto x = __builtin_amdgcn_permlane32_swap(__float_as_uint(ls), __float_as_uint(ls), false, false); ls = __uint_as_float(x[0]) + __uint_as_float(x[1]); }
	v_sub_f32_e32 v17, v89, v20
	v_mul_f32_e32 v18, 0x3e38aa3b, v28
	v_fma_f32 v28, |v17|, v91, v18
	v_sub_f32_e32 v17, v89, v21
	v_mul_f32_e32 v18, 0x3e38aa3b, v29
	v_max3_f32 v16, v32, v24, v25
	v_fma_f32 v29, |v17|, v91, v18
	v_sub_f32_e32 v17, v89, v22
	v_mul_f32_e32 v18, 0x3e38aa3b, v30
	v_max3_f32 v16, v16, v26, v27
	v_fma_f32 v30, |v17|, v91, v18
	v_sub_f32_e32 v17, v89, v23
	v_mul_f32_e32 v18, 0x3e38aa3b, v31
	v_max3_f32 v16, v16, v28, v29
	v_fma_f32 v31, |v17|, v91, v18
	v_max3_f32 v32, v16, v30, v31
	ds_read_b128 v[16:19], v88 offset:512
	ds_read_b128 v[20:23], v88 offset:544
	v_mul_f32_e32 v0, 0x3e38aa3b, v0
	v_mul_f32_e32 v2, 0x3e38aa3b, v2
	s_waitcnt lgkmcnt(1)
	v_sub_f32_e32 v16, v89, v16
	v_fma_f32 v0, |v16|, v91, v0
	v_sub_f32_e32 v17, v89, v17
	v_add_f32_e32 v16, v153, v0
	v_mul_f32_e32 v0, 0x3e38aa3b, v1
	v_fma_f32 v0, |v17|, v91, v0
	v_sub_f32_e32 v1, v89, v18
	v_add_f32_e32 v17, v154, v0
	v_fma_f32 v1, |v1|, v91, v2
	v_mul_f32_e32 v2, 0x3e38aa3b, v3
	v_max3_f32 v0, v32, v16, v17
	v_add_f32_e32 v18, v155, v1
	v_sub_f32_e32 v1, v89, v19
	v_fma_f32 v1, |v1|, v91, v2
	v_mul_f32_e32 v2, 0x3e38aa3b, v4
	v_mul_f32_e32 v8, 0x3e38aa3b, v8
	v_add_f32_e32 v19, v156, v1
	s_waitcnt lgkmcnt(0)
	v_sub_f32_e32 v1, v89, v20
	v_fma_f32 v1, |v1|, v91, v2
	v_mul_f32_e32 v2, 0x3e38aa3b, v5
	v_max3_f32 v0, v0, v18, v19
	v_add_f32_e32 v20, v157, v1
	v_sub_f32_e32 v1, v89, v21
	v_fma_f32 v1, |v1|, v91, v2
	s_nop 1
	v_add_f32_e32 v21, v158, v1
	v_max3_f32 v4, v0, v20, v21
	v_sub_f32_e32 v0, v89, v22
	v_mul_f32_e32 v1, 0x3e38aa3b, v6
	v_fma_f32 v0, |v0|, v91, v1
	v_mul_f32_e32 v1, 0x3e38aa3b, v7
	s_nop 0
	v_add_f32_e32 v22, v159, v0
	v_sub_f32_e32 v0, v89, v23
	v_fma_f32 v5, |v0|, v91, v1
	ds_read_b128 v[0:3], v88 offset:576
	s_nop 1
	v_add_f32_e32 v23, v162, v5
	v_max3_f32 v32, v4, v22, v23
	ds_read_b128 v[4:7], v88 offset:608
	s_waitcnt lgkmcnt(1)
	v_sub_f32_e32 v0, v89, v0
	v_fma_f32 v0, |v0|, v91, v8
	v_sub_f32_e32 v1, v89, v1
	v_mul_f32_e32 v8, 0x3e38aa3b, v9
	v_add_f32_e32 v0, v163, v0
	v_fma_f32 v1, |v1|, v91, v8
	v_sub_f32_e32 v2, v89, v2
	v_mul_f32_e32 v9, 0x3e38aa3b, v10
	v_add_f32_e32 v1, v227, v1
	v_fma_f32 v2, |v2|, v91, v9
	v_sub_f32_e32 v3, v89, v3
	v_mul_f32_e32 v9, 0x3e38aa3b, v11
	v_add_f32_e32 v2, v228, v2
	v_fma_f32 v3, |v3|, v91, v9
	s_waitcnt lgkmcnt(0)
	v_sub_f32_e32 v4, v89, v4
	v_mul_f32_e32 v9, 0x3e38aa3b, v12
	v_add_f32_e32 v3, v229, v3
	v_fma_f32 v4, |v4|, v91, v9
	v_sub_f32_e32 v5, v89, v5
	v_mul_f32_e32 v9, 0x3e38aa3b, v13
	v_add_f32_e32 v4, v230, v4
	v_fma_f32 v5, |v5|, v91, v9
	v_sub_f32_e32 v6, v89, v6
	v_mul_f32_e32 v9, 0x3e38aa3b, v14
	v_max3_f32 v8, v32, v0, v1
	v_add_f32_e32 v5, v231, v5
	v_fma_f32 v6, |v6|, v91, v9
	v_sub_f32_e32 v7, v89, v7
	v_mul_f32_e32 v9, 0x3e38aa3b, v15
	v_max3_f32 v8, v8, v2, v3
	v_add_f32_e32 v6, v232, v6
	v_fma_f32 v7, |v7|, v91, v9
	v_max3_f32 v8, v8, v4, v5
	s_nop 0
	v_add_f32_e32 v7, v233, v7
	v_max3_f32 v8, v8, v6, v7
	v_mov_b32_e32 v9, v8
	s_nop 1
	v_permlane32_swap_b32_e32 v8, v9
	v_max_f32_e32 v9, v9, v9
	v_max_f32_e32 v8, v8, v8
	v_max_f32_e32 v32, v8, v9
	v_sub_f32_e32 v8, v80, v32
	v_exp_f32_e32 v8, v8
	v_sub_f32_e32 v9, v81, v32
	v_exp_f32_e32 v9, v9
	v_sub_f32_e32 v10, v82, v32
	v_exp_f32_e32 v10, v10
	v_sub_f32_e32 v11, v83, v32
	v_exp_f32_e32 v11, v11
	v_sub_f32_e32 v12, v84, v32
	v_exp_f32_e32 v12, v12
	v_sub_f32_e32 v13, v85, v32
	v_add_f32_e32 v80, 0, v8
	v_exp_f32_e32 v13, v13
	v_sub_f32_e32 v14, v86, v32
	v_add_f32_e32 v80, v9, v80
	v_exp_f32_e32 v14, v14
	v_sub_f32_e32 v15, v87, v32
	v_add_f32_e32 v80, v10, v80
	v_exp_f32_e32 v15, v15
	v_sub_f32_e32 v72, v72, v32
	v_add_f32_e32 v80, v11, v80
	v_exp_f32_e32 v72, v72
	v_sub_f32_e32 v73, v73, v32
	v_add_f32_e32 v80, v12, v80
	v_exp_f32_e32 v73, v73
	v_sub_f32_e32 v74, v74, v32
	v_add_f32_e32 v80, v13, v80
	v_exp_f32_e32 v74, v74
	v_sub_f32_e32 v75, v75, v32
	v_add_f32_e32 v80, v14, v80
	v_exp_f32_e32 v75, v75
	v_sub_f32_e32 v76, v76, v32
	v_add_f32_e32 v80, v15, v80
	v_exp_f32_e32 v76, v76
	v_sub_f32_e32 v77, v77, v32
	v_add_f32_e32 v80, v72, v80
	v_exp_f32_e32 v77, v77
	v_sub_f32_e32 v78, v78, v32
	v_add_f32_e32 v80, v73, v80
	v_exp_f32_e32 v78, v78
	v_add_f32_e32 v80, v74, v80
	v_sub_f32_e32 v79, v79, v32
	v_add_f32_e32 v80, v75, v80
	v_exp_f32_e32 v79, v79
	v_add_f32_e32 v80, v76, v80
	v_add_f32_e32 v80, v77, v80
	v_add_f32_e32 v80, v78, v80
	v_add_f32_e32 v80, v79, v80
	v_sub_f32_e32 v64, v64, v32
	v_exp_f32_e32 v64, v64
	v_sub_f32_e32 v65, v65, v32
	v_exp_f32_e32 v65, v65
	v_sub_f32_e32 v66, v66, v32
	v_exp_f32_e32 v66, v66
	v_sub_f32_e32 v67, v67, v32
	v_exp_f32_e32 v67, v67
	v_sub_f32_e32 v68, v68, v32
	v_exp_f32_e32 v68, v68
	v_sub_f32_e32 v69, v69, v32
	v_add_f32_e32 v80, v64, v80
	v_exp_f32_e32 v69, v69
	v_sub_f32_e32 v70, v70, v32
	v_add_f32_e32 v80, v65, v80
	v_exp_f32_e32 v70, v70
	v_sub_f32_e32 v71, v71, v32
	v_add_f32_e32 v80, v66, v80
	v_exp_f32_e32 v71, v71
	v_sub_f32_e32 v56, v56, v32
	v_add_f32_e32 v80, v67, v80
	v_exp_f32_e32 v56, v56
	v_sub_f32_e32 v57, v57, v32
	v_add_f32_e32 v80, v68, v80
	v_exp_f32_e32 v57, v57
	v_sub_f32_e32 v58, v58, v32
	v_add_f32_e32 v80, v69, v80
	v_exp_f32_e32 v58, v58
	v_sub_f32_e32 v59, v59, v32
	v_add_f32_e32 v80, v70, v80
	v_exp_f32_e32 v59, v59
	v_sub_f32_e32 v60, v60, v32
	v_add_f32_e32 v80, v71, v80
	v_exp_f32_e32 v60, v60
	v_sub_f32_e32 v61, v61, v32
	v_add_f32_e32 v80, v56, v80
	v_exp_f32_e32 v61, v61
	v_sub_f32_e32 v62, v62, v32
	v_add_f32_e32 v80, v57, v80
	v_exp_f32_e32 v62, v62
	v_add_f32_e32 v80, v58, v80
	v_sub_f32_e32 v63, v63, v32
	v_add_f32_e32 v80, v59, v80
	v_exp_f32_e32 v63, v63
	v_add_f32_e32 v80, v60, v80
	v_add_f32_e32 v80, v61, v80
; #define SBAR() __builtin_amdgcn_sched_barrier(0)
; DI int v_rd_base(int lane) { return ((lane & 3) << 3) | (((lane >> 2) & 3) << 6) | (((lane >> 4) & 1) << 5) | (((lane >> 5) & 1) << 8); }
; DI s16x4 vtr(const char* p) { return __builtin_bit_cast(s16x4, __builtin_amdgcn_ds_read_tr16_b64_v4i16((LAS v4i16_t*)(uintptr_t)p)); }
; DI void unit(const bf16* __restrict__ QKV, const int* __restrict__ pos, bf16* __restrict__ OA, float* __restrict__ LSE,
;              int b, int h, int d, int r, int qb, float slope, char* lds) {
;     ...
;   float ls = 0.f;
; #pragma unroll
;   for (int ta = 0; ta < 5; ++ta)
; #pragma unroll
;     for (int rr = 0; rr < 16; ++rr) { p[ta][rr] = __builtin_amdgcn_exp2f(p[ta][rr] - mx); ls += p[ta][rr]; if (rr == 15) SBAR(); }
;   { auto x = __builtin_amdgcn_permlane32_swap(__float_as_uint(ls), __float_as_uint(ls), false, false); ls = __uint_as_float(x[0]) + __uint_as_float(x[1]); }
;   f32x16 o[2] = {};
;   const char* vb = V_lds + att::v_rd_base(lane) + wid * 2 * 2048;
; #pragma unroll
;   for (int ta = 0; ta < 5; ++ta) {
;     bf16x8 pa0, pa1; PK4(p[ta], 0, pa0); PK4(p[ta], 8, pa1);
; #pragma unroll
;     for (int d0 = 0; d0 < 2; ++d0) {
;       const s16x4 l0 = vtr(vb + (2 * ta) * 2048 + d0 * 512), h0 = vtr(vb + (2 * ta) * 2048 + 1024 + d0 * 512);
;       const s16x4 l1 = vtr(vb + (2 * ta + 1) * 2048 + d0 * 512), h1 = vtr(vb + (2 * ta + 1) * 2048 + 1024 + d0 * 512);
;       o[d0] = __builtin_amdgcn_mfma_f32_32x32x16_bf16((bf16x8){l0[0], l0[1], l0[2], l0[3], h0[0], h0[1], h0[2], h0[3]}, pa0, o[d0], 0, 0, 0);
;       o[d0] = __builtin_amdgcn_mfma_f32_32x32x16_bf16((bf16x8){l1[0], l1[1], l1[2], l1[3], h1[0], h1[1], h1[2], h1[3]}, pa1, o[d0], 0, 0, 0);
	v_add_f32_e32 v80, v62, v80
	v_add_f32_e32 v80, v63, v80
	v_sub_f32_e32 v40, v40, v32
	v_exp_f32_e32 v87, v40
	v_sub_f32_e32 v40, v41, v32
	v_sub_f32_e32 v48, v48, v32
	v_exp_f32_e32 v88, v40
	v_sub_f32_e32 v40, v42, v32
	v_exp_f32_e32 v81, v48
	v_sub_f32_e32 v48, v49, v32
	v_exp_f32_e32 v89, v40
	v_sub_f32_e32 v40, v43, v32
	v_exp_f32_e32 v82, v48
	v_sub_f32_e32 v48, v50, v32
	v_exp_f32_e32 v90, v40
	v_sub_f32_e32 v40, v44, v32
	v_exp_f32_e32 v83, v48
	v_sub_f32_e32 v48, v51, v32
	v_exp_f32_e32 v91, v40
	v_sub_f32_e32 v40, v45, v32
	v_exp_f32_e32 v84, v48
	v_sub_f32_e32 v48, v52, v32
	v_exp_f32_e32 v100, v40
	v_sub_f32_e32 v40, v46, v32
	v_exp_f32_e32 v85, v48
	v_sub_f32_e32 v48, v53, v32
	v_exp_f32_e32 v101, v40
	v_add_f32_e32 v40, v81, v80
	v_exp_f32_e32 v86, v48
	v_sub_f32_e32 v48, v54, v32
	v_add_f32_e32 v40, v82, v40
	v_exp_f32_e32 v54, v48
	v_sub_f32_e32 v48, v55, v32
	v_add_f32_e32 v40, v83, v40
	v_exp_f32_e32 v55, v48
	v_add_f32_e32 v40, v84, v40
	v_add_f32_e32 v40, v85, v40
	v_add_f32_e32 v40, v86, v40
	v_add_f32_e32 v40, v54, v40
	v_add_f32_e32 v40, v55, v40
	v_add_f32_e32 v40, v87, v40
	v_add_f32_e32 v40, v88, v40
	v_add_f32_e32 v40, v89, v40
	v_sub_f32_e32 v41, v47, v32
	v_add_f32_e32 v40, v90, v40
	v_exp_f32_e32 v80, v41
	v_add_f32_e32 v40, v91, v40
	v_add_f32_e32 v40, v100, v40
	v_add_f32_e32 v40, v101, v40
	v_add_f32_e32 v40, v80, v40
	v_sub_f32_e32 v24, v24, v32
	v_exp_f32_e32 v109, v24
	v_sub_f32_e32 v24, v25, v32
	v_sub_f32_e32 v41, v116, v32
	v_exp_f32_e32 v110, v24
	v_sub_f32_e32 v24, v26, v32
	v_exp_f32_e32 v102, v41
	v_sub_f32_e32 v33, v33, v32
	v_exp_f32_e32 v111, v24
	v_sub_f32_e32 v24, v27, v32
	v_exp_f32_e32 v33, v33
	v_sub_f32_e32 v34, v34, v32
	v_exp_f32_e32 v112, v24
	v_sub_f32_e32 v24, v28, v32
	v_exp_f32_e32 v103, v34
	v_sub_f32_e32 v34, v35, v32
	v_exp_f32_e32 v113, v24
	v_sub_f32_e32 v24, v29, v32
	v_exp_f32_e32 v104, v34
	v_sub_f32_e32 v34, v36, v32
	v_exp_f32_e32 v114, v24
	v_sub_f32_e32 v24, v30, v32
	v_exp_f32_e32 v105, v34
	v_sub_f32_e32 v34, v37, v32
	v_exp_f32_e32 v115, v24
	v_add_f32_e32 v24, v102, v40
	v_exp_f32_e32 v106, v34
	v_sub_f32_e32 v34, v38, v32
	v_add_f32_e32 v24, v33, v24
	v_exp_f32_e32 v107, v34
	v_sub_f32_e32 v34, v39, v32
	v_add_f32_e32 v24, v103, v24
	v_exp_f32_e32 v108, v34
	v_add_f32_e32 v24, v104, v24
	v_add_f32_e32 v24, v105, v24
	v_add_f32_e32 v24, v106, v24
	v_add_f32_e32 v24, v107, v24
	v_add_f32_e32 v24, v108, v24
	v_add_f32_e32 v24, v109, v24
	v_add_f32_e32 v24, v110, v24
	v_add_f32_e32 v24, v111, v24
	v_sub_f32_e32 v25, v31, v32
	v_add_f32_e32 v24, v112, v24
	v_exp_f32_e32 v116, v25
	v_add_f32_e32 v24, v113, v24
	v_add_f32_e32 v24, v114, v24
	v_add_f32_e32 v24, v115, v24
	v_add_f32_e32 v24, v116, v24
	v_sub_f32_e32 v0, v0, v32
	v_exp_f32_e32 v125, v0
	v_sub_f32_e32 v0, v1, v32
	v_sub_f32_e32 v16, v16, v32
	v_exp_f32_e32 v126, v0
	v_sub_f32_e32 v0, v2, v32
	v_exp_f32_e32 v117, v16
	v_sub_f32_e32 v16, v17, v32
	v_exp_f32_e32 v127, v0
	v_sub_f32_e32 v0, v3, v32
	v_exp_f32_e32 v118, v16
	v_sub_f32_e32 v16, v18, v32
	v_exp_f32_e32 v128, v0
	v_sub_f32_e32 v0, v4, v32
	v_exp_f32_e32 v119, v16
	v_sub_f32_e32 v16, v19, v32
	v_exp_f32_e32 v129, v0
	v_sub_f32_e32 v0, v5, v32
	v_exp_f32_e32 v120, v16
	v_sub_f32_e32 v16, v20, v32
	v_exp_f32_e32 v130, v0
	v_sub_f32_e32 v0, v6, v32
	v_exp_f32_e32 v121, v16
	v_sub_f32_e32 v16, v21, v32
	v_exp_f32_e32 v131, v0
	v_add_f32_e32 v0, v117, v24
	v_exp_f32_e32 v122, v16
	v_sub_f32_e32 v16, v22, v32
	v_add_f32_e32 v0, v118, v0
	v_exp_f32_e32 v123, v16
	v_sub_f32_e32 v16, v23, v32
	v_add_f32_e32 v0, v119, v0
	v_exp_f32_e32 v124, v16
	v_add_f32_e32 v0, v120, v0
	v_add_f32_e32 v0, v121, v0
	v_add_f32_e32 v0, v122, v0
	v_add_f32_e32 v0, v123, v0
	v_add_f32_e32 v0, v124, v0
	v_add_f32_e32 v0, v125, v0
	v_add_f32_e32 v0, v126, v0
	v_add_f32_e32 v0, v127, v0
	v_sub_f32_e32 v1, v7, v32
	v_add_f32_e32 v0, v128, v0
	v_exp_f32_e32 v132, v1
	v_add_f32_e32 v0, v129, v0
	v_add_f32_e32 v0, v130, v0
	v_add_f32_e32 v0, v131, v0
	v_add_f32_e32 v133, v132, v0
	v_lshlrev_b32_e32 v0, 3, v98
	v_and_b32_e32 v1, 24, v0
	v_lshlrev_b32_e32 v2, 4, v98
	v_lshlrev_b32_e32 v3, 1, v98
	v_and_b32_e32 v2, 0xc0, v2
	v_and_b32_e32 v3, 32, v3
	v_add_u32_e32 v1, 0, v1
	v_and_b32_e32 v0, 0x100, v0
	v_add3_u32 v1, v1, v2, v3
	v_add3_u32 v99, v1, v0, v99
	v_cvt_pk_bf16_f32 v0, v8, v9
	v_cvt_pk_bf16_f32 v1, v10, v11
	v_cvt_pk_bf16_f32 v2, v12, v13
	v_cvt_pk_bf16_f32 v3, v14, v15
	v_cvt_pk_bf16_f32 v34, v72, v73
	v_cvt_pk_bf16_f32 v35, v74, v75
	v_cvt_pk_bf16_f32 v36, v76, v77
	v_cvt_pk_bf16_f32 v37, v78, v79
	ds_read_b64_tr_b16 v[4:5], v99 offset:49152
	ds_read_b64_tr_b16 v[6:7], v99 offset:50176
	v_permlane32_swap_b32_e32 v0, v2
	v_permlane32_swap_b32_e32 v1, v3
	ds_read_b64_tr_b16 v[10:11], v99 offset:50688
	ds_read_b64_tr_b16 v[8:9], v99 offset:49664
	s_waitcnt lgkmcnt(2)
	v_mfma_f32_32x32x16_bf16 v[16:31], v[4:7], v[0:3], 0
	ds_read_b64_tr_b16 v[4:5], v99 offset:51200
	ds_read_b64_tr_b16 v[6:7], v99 offset:52224
	v_permlane32_swap_b32_e32 v34, v36
	v_permlane32_swap_b32_e32 v35, v37
	ds_read_b64_tr_b16 v[40:41], v99 offset:52736
	ds_read_b64_tr_b16 v[38:39], v99 offset:51712
	v_mov_b32_e32 v72, v133
	s_waitcnt lgkmcnt(2)
; #define SBAR() __builtin_amdgcn_sched_barrier(0)
; DI int v_rd_base(int lane) { return ((lane & 3) << 3) | (((lane >> 2) & 3) << 6) | (((lane >> 4) & 1) << 5) | (((lane >> 5) & 1) << 8); }
; DI s16x4 vtr(const char* p) { return __builtin_bit_cast(s16x4, __builtin_amdgcn_ds_read_tr16_b64_v4i16((LAS v4i16_t*)(uintptr_t)p)); }
; DI void unit(const bf16* __restrict__ QKV, const int* __restrict__ pos, bf16* __restrict__ OA, float* __restrict__ LSE,
;              int b, int h, int d, int r, int qb, float slope, char* lds) {
;     ...
;   f32x16 o[2] = {};
;   const char* vb = V_lds + att::v_rd_base(lane) + wid * 2 * 2048;
; #pragma unroll
;   for (int ta = 0; ta < 5; ++ta) {
;     bf16x8 pa0, pa1; PK4(p[ta], 0, pa0); PK4(p[ta], 8, pa1);
; #pragma unroll
;     for (int d0 = 0; d0 < 2; ++d0) {
;       const s16x4 l0 = vtr(vb + (2 * ta) * 2048 + d0 * 512), h0 = vtr(vb + (2 * ta) * 2048 + 1024 + d0 * 512);
;       const s16x4 l1 = vtr(vb + (2 * ta + 1) * 2048 + d0 * 512), h1 = vtr(vb + (2 * ta + 1) * 2048 + 1024 + d0 * 512);
;       o[d0] = __builtin_amdgcn_mfma_f32_32x32x16_bf16((bf16x8){l0[0], l0[1], l0[2], l0[3], h0[0], h0[1], h0[2], h0[3]}, pa0, o[d0], 0, 0, 0);
;       o[d0] = __builtin_amdgcn_mfma_f32_32x32x16_bf16((bf16x8){l1[0], l1[1], l1[2], l1[3], h1[0], h1[1], h1[2], h1[3]}, pa1, o[d0], 0, 0, 0);
;     }
;     SBAR();
;   }
;   if (hi == 0) LSE[(size_t)(b * SEQ + tq) * 8 + h] = (mx + __builtin_amdgcn_logf(ls)) * 0.6931471805599453f;
	v_mfma_f32_32x32x16_bf16 v[16:31], v[4:7], v[34:37], v[16:31]
	v_permlane32_swap_b32_e32 v133, v72
	v_add_u32_e32 v73, 0xc000, v99
	v_mfma_f32_32x32x16_bf16 v[0:15], v[8:11], v[0:3], 0
	s_waitcnt lgkmcnt(0)
	v_mfma_f32_32x32x16_bf16 v[0:15], v[38:41], v[34:37], v[0:15]
	v_cvt_pk_bf16_f32 v34, v64, v65
	v_cvt_pk_bf16_f32 v35, v66, v67
	v_cvt_pk_bf16_f32 v36, v68, v69
	v_cvt_pk_bf16_f32 v37, v70, v71
	v_cvt_pk_bf16_f32 v38, v56, v57
	v_cvt_pk_bf16_f32 v39, v58, v59
	v_cvt_pk_bf16_f32 v40, v60, v61
	v_cvt_pk_bf16_f32 v41, v62, v63
	ds_read_b64_tr_b16 v[42:43], v99 offset:53248
	ds_read_b64_tr_b16 v[44:45], v99 offset:54272
	ds_read_b64_tr_b16 v[48:49], v99 offset:54784
	ds_read_b64_tr_b16 v[46:47], v99 offset:53760
	v_permlane32_swap_b32_e32 v34, v36
	v_permlane32_swap_b32_e32 v35, v37
	v_permlane32_swap_b32_e32 v38, v40
	s_waitcnt lgkmcnt(2)
	v_mfma_f32_32x32x16_bf16 v[16:31], v[42:45], v[34:37], v[16:31]
	ds_read_b64_tr_b16 v[42:43], v99 offset:55296
	ds_read_b64_tr_b16 v[44:45], v99 offset:56320
	ds_read_b64_tr_b16 v[52:53], v99 offset:56832
	ds_read_b64_tr_b16 v[50:51], v99 offset:55808
	v_permlane32_swap_b32_e32 v39, v41
	s_waitcnt lgkmcnt(4)
	v_mfma_f32_32x32x16_bf16 v[0:15], v[46:49], v[34:37], v[0:15]
	s_waitcnt lgkmcnt(2)
	v_mfma_f32_32x32x16_bf16 v[16:31], v[42:45], v[38:41], v[16:31]
	s_waitcnt lgkmcnt(0)
	v_mfma_f32_32x32x16_bf16 v[0:15], v[50:53], v[38:41], v[0:15]
	v_cvt_pk_bf16_f32 v34, v81, v82
	v_cvt_pk_bf16_f32 v35, v83, v84
	v_cvt_pk_bf16_f32 v36, v85, v86
	v_cvt_pk_bf16_f32 v37, v54, v55
	v_cvt_pk_bf16_f32 v38, v87, v88
	v_cvt_pk_bf16_f32 v39, v89, v90
	v_cvt_pk_bf16_f32 v40, v91, v100
	v_cvt_pk_bf16_f32 v41, v101, v80
	ds_read_b64_tr_b16 v[42:43], v99 offset:57344
	ds_read_b64_tr_b16 v[44:45], v99 offset:58368
	ds_read_b64_tr_b16 v[48:49], v99 offset:58880
	ds_read_b64_tr_b16 v[46:47], v99 offset:57856
	v_permlane32_swap_b32_e32 v34, v36
	v_permlane32_swap_b32_e32 v35, v37
	v_permlane32_swap_b32_e32 v38, v40
	s_waitcnt lgkmcnt(2)
	v_mfma_f32_32x32x16_bf16 v[16:31], v[42:45], v[34:37], v[16:31]
	ds_read_b64_tr_b16 v[42:43], v99 offset:59392
	ds_read_b64_tr_b16 v[44:45], v99 offset:60416
	ds_read_b64_tr_b16 v[52:53], v99 offset:60928
	ds_read_b64_tr_b16 v[50:51], v99 offset:59904
	v_permlane32_swap_b32_e32 v39, v41
	s_waitcnt lgkmcnt(4)
	v_mfma_f32_32x32x16_bf16 v[0:15], v[46:49], v[34:37], v[0:15]
	s_waitcnt lgkmcnt(2)
	v_mfma_f32_32x32x16_bf16 v[16:31], v[42:45], v[38:41], v[16:31]
	s_waitcnt lgkmcnt(0)
	v_mfma_f32_32x32x16_bf16 v[0:15], v[50:53], v[38:41], v[0:15]
	v_cvt_pk_bf16_f32 v34, v102, v33
	v_cvt_pk_bf16_f32 v35, v103, v104
	v_cvt_pk_bf16_f32 v36, v105, v106
	v_cvt_pk_bf16_f32 v37, v107, v108
	v_cvt_pk_bf16_f32 v38, v109, v110
	v_cvt_pk_bf16_f32 v39, v111, v112
	v_cvt_pk_bf16_f32 v40, v113, v114
	v_cvt_pk_bf16_f32 v41, v115, v116
	ds_read_b64_tr_b16 v[42:43], v99 offset:61440
	ds_read_b64_tr_b16 v[44:45], v99 offset:62464
	ds_read_b64_tr_b16 v[48:49], v99 offset:62976
	ds_read_b64_tr_b16 v[46:47], v99 offset:61952
	v_permlane32_swap_b32_e32 v34, v36
	v_permlane32_swap_b32_e32 v35, v37
	v_permlane32_swap_b32_e32 v38, v40
	s_waitcnt lgkmcnt(2)
	v_mfma_f32_32x32x16_bf16 v[16:31], v[42:45], v[34:37], v[16:31]
	ds_read_b64_tr_b16 v[42:43], v99 offset:63488
	ds_read_b64_tr_b16 v[44:45], v99 offset:64512
	ds_read_b64_tr_b16 v[52:53], v99 offset:65024
	ds_read_b64_tr_b16 v[50:51], v99 offset:64000
	v_permlane32_swap_b32_e32 v39, v41
	s_waitcnt lgkmcnt(4)
	v_mfma_f32_32x32x16_bf16 v[0:15], v[46:49], v[34:37], v[0:15]
	s_waitcnt lgkmcnt(2)
	v_mfma_f32_32x32x16_bf16 v[16:31], v[42:45], v[38:41], v[16:31]
	s_waitcnt lgkmcnt(0)
	v_mfma_f32_32x32x16_bf16 v[0:15], v[50:53], v[38:41], v[0:15]
	v_cvt_pk_bf16_f32 v34, v117, v118
	v_cvt_pk_bf16_f32 v35, v119, v120
	v_cvt_pk_bf16_f32 v36, v121, v122
	v_cvt_pk_bf16_f32 v37, v123, v124
	v_cvt_pk_bf16_f32 v38, v125, v126
	v_cvt_pk_bf16_f32 v39, v127, v128
	v_cvt_pk_bf16_f32 v40, v129, v130
	v_cvt_pk_bf16_f32 v41, v131, v132
	ds_read_b64_tr_b16 v[42:43], v73 offset:16384
	ds_read_b64_tr_b16 v[44:45], v73 offset:17408
	ds_read_b64_tr_b16 v[48:49], v73 offset:17920
	ds_read_b64_tr_b16 v[46:47], v73 offset:16896
	v_permlane32_swap_b32_e32 v34, v36
	v_permlane32_swap_b32_e32 v35, v37
	v_permlane32_swap_b32_e32 v38, v40
	s_waitcnt lgkmcnt(2)
	v_mfma_f32_32x32x16_bf16 v[16:31], v[42:45], v[34:37], v[16:31]
	ds_read_b64_tr_b16 v[42:43], v73 offset:18432
	ds_read_b64_tr_b16 v[44:45], v73 offset:19456
	ds_read_b64_tr_b16 v[52:53], v73 offset:19968
	ds_read_b64_tr_b16 v[50:51], v73 offset:18944
	v_permlane32_swap_b32_e32 v39, v41
	s_waitcnt lgkmcnt(4)
	v_mfma_f32_32x32x16_bf16 v[0:15], v[46:49], v[34:37], v[0:15]
	s_waitcnt lgkmcnt(2)
	v_mfma_f32_32x32x16_bf16 v[16:31], v[42:45], v[38:41], v[16:31]
	s_waitcnt lgkmcnt(0)
	v_mfma_f32_32x32x16_bf16 v[0:15], v[50:53], v[38:41], v[0:15]
	v_add_f32_e32 v33, v133, v72
	v_cmp_gt_u32_e32 vcc, 32, v98
	s_and_saveexec_b64 s[2:3], vcc
	s_cbranch_execz .LBB0_857
	v_log_f32_e32 v34, v33
	s_lshl_b64 s[4:5], s[14:15], 20
	s_add_u32 s4, s13, s4
	s_addc_u32 s5, s38, s5
	v_add_f32_e32 v32, v32, v34
	v_lshlrev_b64 v[34:35], 5, v[94:95]
	v_lshl_add_u64 v[34:35], s[4:5], 0, v[34:35]
	s_lshl_b32 s8, s48, 2
	v_mul_f32_e32 v32, 0x3f317218, v32
	v_lshl_add_u64 v[34:35], v[34:35], 0, s[8:9]
	global_store_dword v[34:35], v32, off
	s_branch .LBB0_857
